# a14 + ret_local: per-item decay factors computed once per wave into a private LDS table (same cvt-mul-exp sequence) and read with broadcast ds_read_b128; inner loop unrolled
# speedup vs baseline: 1.0045x; 1.0045x over previous
.LBB0_750:
	s_lshr_b32 s0, s16, 4
	s_and_b32 s0, s0, 28
	v_mov_b32_e32 v0, s0
	global_load_dword v31, v0, s[50:51]
	global_load_dword v56, v0, s[52:53]
	v_mov_b32_e32 v0, 0
	s_mov_b32 s0, 0
	v_mov_b32_e32 v82, v78
	v_mov_b32_e32 v83, v77
	v_mov_b32_e32 v84, v76
	v_mov_b32_e32 v1, v0
	v_mov_b32_e32 v2, v0
	v_mov_b32_e32 v3, v0
	v_mov_b32_e32 v4, v0
	v_mov_b32_e32 v5, v0
	v_mov_b32_e32 v6, v0
	v_mov_b32_e32 v7, v0
	v_mov_b32_e32 v8, v0
	v_mov_b32_e32 v9, v0
	v_mov_b32_e32 v10, v0
	v_mov_b32_e32 v11, v0
	v_mov_b32_e32 v12, v0
	v_mov_b32_e32 v13, v0
	v_mov_b32_e32 v14, v0
	v_mov_b32_e32 v15, v0
	v_mov_b32_e32 v16, v0
	v_mov_b32_e32 v17, v0
	v_mov_b32_e32 v18, v0
	v_mov_b32_e32 v19, v0
	v_mov_b32_e32 v20, v0
	v_mov_b32_e32 v21, v0
	v_mov_b32_e32 v22, v0
	v_mov_b32_e32 v23, v0
	v_mov_b32_e32 v24, v0
	v_mov_b32_e32 v25, v0
	v_mov_b32_e32 v26, v0
	v_mov_b32_e32 v27, v0
	v_mov_b32_e32 v28, v0
	s_waitcnt vmcnt(1)
	v_mul_f32_e32 v29, 0x3fb8aa3b, v31
	s_waitcnt vmcnt(0)
	v_mul_f32_e32 v30, 0x3fb8aa3b, v56
	v_fma_f32 v57, v31, s9, -v29
	v_rndne_f32_e32 v58, v29
	v_fma_f32 v59, v56, s9, -v30
	v_rndne_f32_e32 v60, v30
	v_fmac_f32_e32 v57, 0x32a5705f, v31
	v_sub_f32_e32 v29, v29, v58
	v_fmac_f32_e32 v59, 0x32a5705f, v56
	v_sub_f32_e32 v30, v30, v60
	v_add_f32_e32 v29, v29, v57
	v_cvt_i32_f32_e32 v58, v58
	v_add_f32_e32 v30, v30, v59
	v_exp_f32_e32 v57, v29
	v_cvt_i32_f32_e32 v60, v60
	v_exp_f32_e32 v59, v30
	v_cmp_ngt_f32_e32 vcc, s20, v31
	v_ldexp_f32 v57, v57, v58
	v_mov_b32_e32 v29, v0
	v_ldexp_f32 v58, v59, v60
	v_cndmask_b32_e32 v57, 0, v57, vcc
	v_cmp_ngt_f32_e32 vcc, s20, v56
	v_mov_b32_e32 v30, v0
	s_nop 0
	v_cndmask_b32_e32 v58, 0, v58, vcc
	v_cmp_nlt_f32_e32 vcc, s21, v31
	s_nop 1
	v_cndmask_b32_e32 v31, v81, v57, vcc
	v_cmp_nlt_f32_e32 vcc, s21, v56
	v_mul_f32_e32 v85, 0xbfb8aa3b, v31
	v_mov_b32_e32 v31, v0
	v_cndmask_b32_e32 v56, v81, v58, vcc
	v_mul_f32_e32 v86, 0xbfb8aa3b, v56
	s_lshl_b32 s56, s33, 4
	s_add_i32 s56, s56, 0x18000
	v_and_b32_e32 v150, 63, v64
	v_sub_u32_e32 v151, 0x7f, v150
	v_sub_u32_e32 v152, 63, v150
	v_add_u32_e32 v153, 64, v150
	v_cvt_f32_u32_e32 v151, v151
	v_cvt_f32_u32_e32 v152, v152
	v_cvt_f32_u32_e32 v154, v150
	v_cvt_f32_u32_e32 v153, v153
	v_mul_f32_e32 v151, v85, v151
	v_mul_f32_e32 v152, v85, v152
	v_mul_f32_e32 v154, v86, v154
	v_mul_f32_e32 v153, v86, v153
	v_exp_f32_e32 v151, v151
	v_exp_f32_e32 v152, v152
	v_exp_f32_e32 v154, v154
	v_exp_f32_e32 v153, v153
	v_lshl_add_u32 v155, v150, 2, s56
	v_lshl_add_u32 v156, v74, 2, s56
	ds_write_b32 v155, v151
	ds_write_b32 v155, v152 offset:256
	ds_write_b32 v155, v154 offset:512
	ds_write_b32 v155, v153 offset:768
	ds_read_b128 v[60:63], v84
	ds_read_b128 v[56:59], v84 offset:32
	ds_read_u16 v96, v82
	ds_read_u16 v97, v82 offset:144
	ds_read_u16 v98, v82 offset:288
	ds_read_u16 v99, v82 offset:432
	ds_read_u16 v100, v82 offset:1152
	ds_read_u16 v101, v82 offset:1296
	ds_read_u16 v102, v82 offset:1440
	ds_read_u16 v103, v82 offset:1584
	ds_read_u16 v112, v82 offset:2304
	ds_read_u16 v113, v82 offset:2448
	ds_read_u16 v114, v82 offset:2592
	ds_read_u16 v115, v82 offset:2736
	ds_read_u16 v116, v82 offset:3456
	ds_read_u16 v117, v82 offset:3600
	ds_read_u16 v118, v82 offset:3744
	ds_read_u16 v119, v82 offset:3888
	ds_read_b128 v[160:163], v156
	ds_read_b128 v[164:167], v156 offset:32
	ds_read_b128 v[168:171], v156 offset:512
	ds_read_b128 v[172:175], v156 offset:544
	ds_read_b128 v[176:179], v156 offset:64
	ds_read_b128 v[180:183], v156 offset:96
	ds_read_b128 v[184:187], v156 offset:576
	ds_read_b128 v[188:191], v156 offset:608
	s_waitcnt lgkmcnt(4)
	v_lshlrev_b32_e32 v88, 16, v96
	v_lshlrev_b32_e32 v89, 16, v97
	v_lshlrev_b32_e32 v90, 16, v98
	v_lshlrev_b32_e32 v91, 16, v99
	v_lshlrev_b32_e32 v92, 16, v100
	v_lshlrev_b32_e32 v93, 16, v101
	v_lshlrev_b32_e32 v94, 16, v102
	v_lshlrev_b32_e32 v95, 16, v103
	v_pk_mul_f32 v[160:161], v[160:161], v[88:89]
	v_pk_mul_f32 v[162:163], v[162:163], v[90:91]
	v_pk_mul_f32 v[164:165], v[164:165], v[92:93]
	v_pk_mul_f32 v[166:167], v[166:167], v[94:95]
	v_pk_mul_f32 v[168:169], v[168:169], v[88:89]
	v_pk_mul_f32 v[170:171], v[170:171], v[90:91]
	v_pk_mul_f32 v[172:173], v[172:173], v[92:93]
	v_pk_mul_f32 v[174:175], v[174:175], v[94:95]
	v_cvt_pk_bf16_f32 v104, v160, v161
	v_cvt_pk_bf16_f32 v105, v162, v163
	v_cvt_pk_bf16_f32 v106, v164, v165
	v_cvt_pk_bf16_f32 v107, v166, v167
	v_cvt_pk_bf16_f32 v108, v168, v169
	v_cvt_pk_bf16_f32 v109, v170, v171
	v_cvt_pk_bf16_f32 v110, v172, v173
	v_cvt_pk_bf16_f32 v111, v174, v175
	s_nop 1
	v_mfma_f32_32x32x16_bf16 v[16:31], v[60:63], v[104:107], v[16:31]
	v_mfma_f32_32x32x16_bf16 v[0:15], v[60:63], v[108:111], v[0:15]
	s_waitcnt lgkmcnt(0)
	v_lshlrev_b32_e32 v88, 16, v112
	v_lshlrev_b32_e32 v89, 16, v113
	v_lshlrev_b32_e32 v90, 16, v114
	v_lshlrev_b32_e32 v91, 16, v115
	v_lshlrev_b32_e32 v92, 16, v116
	v_lshlrev_b32_e32 v93, 16, v117
	v_lshlrev_b32_e32 v94, 16, v118
	v_lshlrev_b32_e32 v95, 16, v119
	v_pk_mul_f32 v[176:177], v[176:177], v[88:89]
	v_pk_mul_f32 v[178:179], v[178:179], v[90:91]
	v_pk_mul_f32 v[180:181], v[180:181], v[92:93]
	v_pk_mul_f32 v[182:183], v[182:183], v[94:95]
	v_pk_mul_f32 v[184:185], v[184:185], v[88:89]
	v_pk_mul_f32 v[186:187], v[186:187], v[90:91]
	v_pk_mul_f32 v[188:189], v[188:189], v[92:93]
	v_pk_mul_f32 v[190:191], v[190:191], v[94:95]
	v_cvt_pk_bf16_f32 v120, v176, v177
	v_cvt_pk_bf16_f32 v121, v178, v179
	v_cvt_pk_bf16_f32 v122, v180, v181
	v_cvt_pk_bf16_f32 v123, v182, v183
	v_cvt_pk_bf16_f32 v124, v184, v185
	v_cvt_pk_bf16_f32 v125, v186, v187
	v_cvt_pk_bf16_f32 v126, v188, v189
	v_cvt_pk_bf16_f32 v127, v190, v191
	s_nop 1
	v_mfma_f32_32x32x16_bf16 v[16:31], v[56:59], v[120:123], v[16:31]
	v_mfma_f32_32x32x16_bf16 v[0:15], v[56:59], v[124:127], v[0:15]
	ds_read_b128 v[60:63], v84 offset:64
	ds_read_b128 v[56:59], v84 offset:96
	ds_read_u16 v96, v82 offset:4608
	ds_read_u16 v97, v82 offset:4752
	ds_read_u16 v98, v82 offset:4896
	ds_read_u16 v99, v82 offset:5040
	ds_read_u16 v100, v82 offset:5760
	ds_read_u16 v101, v82 offset:5904
	ds_read_u16 v102, v82 offset:6048
	ds_read_u16 v103, v82 offset:6192
	ds_read_u16 v112, v82 offset:6912
	ds_read_u16 v113, v82 offset:7056
	ds_read_u16 v114, v82 offset:7200
	ds_read_u16 v115, v82 offset:7344
	ds_read_u16 v116, v82 offset:8064
	ds_read_u16 v117, v82 offset:8208
	ds_read_u16 v118, v82 offset:8352
	ds_read_u16 v119, v82 offset:8496
	ds_read_b128 v[160:163], v156 offset:128
	ds_read_b128 v[164:167], v156 offset:160
	ds_read_b128 v[168:171], v156 offset:640
	ds_read_b128 v[172:175], v156 offset:672
	ds_read_b128 v[176:179], v156 offset:192
	ds_read_b128 v[180:183], v156 offset:224
	ds_read_b128 v[184:187], v156 offset:704
	ds_read_b128 v[188:191], v156 offset:736
	s_waitcnt lgkmcnt(4)
	v_lshlrev_b32_e32 v88, 16, v96
	v_lshlrev_b32_e32 v89, 16, v97
	v_lshlrev_b32_e32 v90, 16, v98
	v_lshlrev_b32_e32 v91, 16, v99
	v_lshlrev_b32_e32 v92, 16, v100
	v_lshlrev_b32_e32 v93, 16, v101
	v_lshlrev_b32_e32 v94, 16, v102
	v_lshlrev_b32_e32 v95, 16, v103
	v_pk_mul_f32 v[160:161], v[160:161], v[88:89]
	v_pk_mul_f32 v[162:163], v[162:163], v[90:91]
	v_pk_mul_f32 v[164:165], v[164:165], v[92:93]
	v_pk_mul_f32 v[166:167], v[166:167], v[94:95]
	v_pk_mul_f32 v[168:169], v[168:169], v[88:89]
	v_pk_mul_f32 v[170:171], v[170:171], v[90:91]
	v_pk_mul_f32 v[172:173], v[172:173], v[92:93]
	v_pk_mul_f32 v[174:175], v[174:175], v[94:95]
	v_cvt_pk_bf16_f32 v104, v160, v161
	v_cvt_pk_bf16_f32 v105, v162, v163
	v_cvt_pk_bf16_f32 v106, v164, v165
	v_cvt_pk_bf16_f32 v107, v166, v167
	v_cvt_pk_bf16_f32 v108, v168, v169
	v_cvt_pk_bf16_f32 v109, v170, v171
	v_cvt_pk_bf16_f32 v110, v172, v173
	v_cvt_pk_bf16_f32 v111, v174, v175
	s_nop 1
	v_mfma_f32_32x32x16_bf16 v[16:31], v[60:63], v[104:107], v[16:31]
	v_mfma_f32_32x32x16_bf16 v[0:15], v[60:63], v[108:111], v[0:15]
	s_waitcnt lgkmcnt(0)
	v_lshlrev_b32_e32 v88, 16, v112
	v_lshlrev_b32_e32 v89, 16, v113
	v_lshlrev_b32_e32 v90, 16, v114
	v_lshlrev_b32_e32 v91, 16, v115
	v_lshlrev_b32_e32 v92, 16, v116
	v_lshlrev_b32_e32 v93, 16, v117
	v_lshlrev_b32_e32 v94, 16, v118
	v_lshlrev_b32_e32 v95, 16, v119
	v_pk_mul_f32 v[176:177], v[176:177], v[88:89]
	v_pk_mul_f32 v[178:179], v[178:179], v[90:91]
	v_pk_mul_f32 v[180:181], v[180:181], v[92:93]
	v_pk_mul_f32 v[182:183], v[182:183], v[94:95]
	v_pk_mul_f32 v[184:185], v[184:185], v[88:89]
	v_pk_mul_f32 v[186:187], v[186:187], v[90:91]
	v_pk_mul_f32 v[188:189], v[188:189], v[92:93]
	v_pk_mul_f32 v[190:191], v[190:191], v[94:95]
	v_cvt_pk_bf16_f32 v120, v176, v177
	v_cvt_pk_bf16_f32 v121, v178, v179
	v_cvt_pk_bf16_f32 v122, v180, v181
	v_cvt_pk_bf16_f32 v123, v182, v183
	v_cvt_pk_bf16_f32 v124, v184, v185
	v_cvt_pk_bf16_f32 v125, v186, v187
	v_cvt_pk_bf16_f32 v126, v188, v189
	v_cvt_pk_bf16_f32 v127, v190, v191
	s_nop 1
	v_mfma_f32_32x32x16_bf16 v[16:31], v[56:59], v[120:123], v[16:31]
	v_mfma_f32_32x32x16_bf16 v[0:15], v[56:59], v[124:127], v[0:15]
	ds_read_b128 v[60:63], v84 offset:128
	ds_read_b128 v[56:59], v84 offset:160
	ds_read_u16 v96, v82 offset:9216
	ds_read_u16 v97, v82 offset:9360
	ds_read_u16 v98, v82 offset:9504
	ds_read_u16 v99, v82 offset:9648
	ds_read_u16 v100, v82 offset:10368
	ds_read_u16 v101, v82 offset:10512
	ds_read_u16 v102, v82 offset:10656
	ds_read_u16 v103, v82 offset:10800
	ds_read_u16 v112, v82 offset:11520
	ds_read_u16 v113, v82 offset:11664
	ds_read_u16 v114, v82 offset:11808
	ds_read_u16 v115, v82 offset:11952
	ds_read_u16 v116, v82 offset:12672
	ds_read_u16 v117, v82 offset:12816
	ds_read_u16 v118, v82 offset:12960
	ds_read_u16 v119, v82 offset:13104
	ds_read_b128 v[160:163], v156 offset:256
	ds_read_b128 v[164:167], v156 offset:288
	ds_read_b128 v[168:171], v156 offset:768
	ds_read_b128 v[172:175], v156 offset:800
	ds_read_b128 v[176:179], v156 offset:320
	ds_read_b128 v[180:183], v156 offset:352
	ds_read_b128 v[184:187], v156 offset:832
	ds_read_b128 v[188:191], v156 offset:864
	s_waitcnt lgkmcnt(4)
	v_lshlrev_b32_e32 v88, 16, v96
	v_lshlrev_b32_e32 v89, 16, v97
	v_lshlrev_b32_e32 v90, 16, v98
	v_lshlrev_b32_e32 v91, 16, v99
	v_lshlrev_b32_e32 v92, 16, v100
	v_lshlrev_b32_e32 v93, 16, v101
	v_lshlrev_b32_e32 v94, 16, v102
	v_lshlrev_b32_e32 v95, 16, v103
	v_pk_mul_f32 v[160:161], v[160:161], v[88:89]
	v_pk_mul_f32 v[162:163], v[162:163], v[90:91]
	v_pk_mul_f32 v[164:165], v[164:165], v[92:93]
	v_pk_mul_f32 v[166:167], v[166:167], v[94:95]
	v_pk_mul_f32 v[168:169], v[168:169], v[88:89]
	v_pk_mul_f32 v[170:171], v[170:171], v[90:91]
	v_pk_mul_f32 v[172:173], v[172:173], v[92:93]
	v_pk_mul_f32 v[174:175], v[174:175], v[94:95]
	v_cvt_pk_bf16_f32 v104, v160, v161
	v_cvt_pk_bf16_f32 v105, v162, v163
	v_cvt_pk_bf16_f32 v106, v164, v165
	v_cvt_pk_bf16_f32 v107, v166, v167
	v_cvt_pk_bf16_f32 v108, v168, v169
	v_cvt_pk_bf16_f32 v109, v170, v171
	v_cvt_pk_bf16_f32 v110, v172, v173
	v_cvt_pk_bf16_f32 v111, v174, v175
	s_nop 1
	v_mfma_f32_32x32x16_bf16 v[16:31], v[60:63], v[104:107], v[16:31]
	v_mfma_f32_32x32x16_bf16 v[0:15], v[60:63], v[108:111], v[0:15]
	s_waitcnt lgkmcnt(0)
	v_lshlrev_b32_e32 v88, 16, v112
	v_lshlrev_b32_e32 v89, 16, v113
	v_lshlrev_b32_e32 v90, 16, v114
	v_lshlrev_b32_e32 v91, 16, v115
	v_lshlrev_b32_e32 v92, 16, v116
	v_lshlrev_b32_e32 v93, 16, v117
	v_lshlrev_b32_e32 v94, 16, v118
	v_lshlrev_b32_e32 v95, 16, v119
	v_pk_mul_f32 v[176:177], v[176:177], v[88:89]
	v_pk_mul_f32 v[178:179], v[178:179], v[90:91]
	v_pk_mul_f32 v[180:181], v[180:181], v[92:93]
	v_pk_mul_f32 v[182:183], v[182:183], v[94:95]
	v_pk_mul_f32 v[184:185], v[184:185], v[88:89]
	v_pk_mul_f32 v[186:187], v[186:187], v[90:91]
	v_pk_mul_f32 v[188:189], v[188:189], v[92:93]
	v_pk_mul_f32 v[190:191], v[190:191], v[94:95]
	v_cvt_pk_bf16_f32 v120, v176, v177
	v_cvt_pk_bf16_f32 v121, v178, v179
	v_cvt_pk_bf16_f32 v122, v180, v181
	v_cvt_pk_bf16_f32 v123, v182, v183
	v_cvt_pk_bf16_f32 v124, v184, v185
	v_cvt_pk_bf16_f32 v125, v186, v187
	v_cvt_pk_bf16_f32 v126, v188, v189
	v_cvt_pk_bf16_f32 v127, v190, v191
	s_nop 1
	v_mfma_f32_32x32x16_bf16 v[16:31], v[56:59], v[120:123], v[16:31]
	v_mfma_f32_32x32x16_bf16 v[0:15], v[56:59], v[124:127], v[0:15]
	ds_read_b128 v[60:63], v84 offset:192
	ds_read_b128 v[56:59], v84 offset:224
	ds_read_u16 v96, v82 offset:13824
	ds_read_u16 v97, v82 offset:13968
	ds_read_u16 v98, v82 offset:14112
	ds_read_u16 v99, v82 offset:14256
	ds_read_u16 v100, v82 offset:14976
	ds_read_u16 v101, v82 offset:15120
	ds_read_u16 v102, v82 offset:15264
	ds_read_u16 v103, v82 offset:15408
	ds_read_u16 v112, v82 offset:16128
	ds_read_u16 v113, v82 offset:16272
	ds_read_u16 v114, v82 offset:16416
	ds_read_u16 v115, v82 offset:16560
	ds_read_u16 v116, v82 offset:17280
	ds_read_u16 v117, v82 offset:17424
	ds_read_u16 v118, v82 offset:17568
	ds_read_u16 v119, v82 offset:17712
	ds_read_b128 v[160:163], v156 offset:384
	ds_read_b128 v[164:167], v156 offset:416
	ds_read_b128 v[168:171], v156 offset:896
	ds_read_b128 v[172:175], v156 offset:928
	ds_read_b128 v[176:179], v156 offset:448
	ds_read_b128 v[180:183], v156 offset:480
	ds_read_b128 v[184:187], v156 offset:960
	ds_read_b128 v[188:191], v156 offset:992
	s_waitcnt lgkmcnt(4)
	v_lshlrev_b32_e32 v88, 16, v96
	v_lshlrev_b32_e32 v89, 16, v97
	v_lshlrev_b32_e32 v90, 16, v98
	v_lshlrev_b32_e32 v91, 16, v99
	v_lshlrev_b32_e32 v92, 16, v100
	v_lshlrev_b32_e32 v93, 16, v101
	v_lshlrev_b32_e32 v94, 16, v102
	v_lshlrev_b32_e32 v95, 16, v103
	v_pk_mul_f32 v[160:161], v[160:161], v[88:89]
	v_pk_mul_f32 v[162:163], v[162:163], v[90:91]
	v_pk_mul_f32 v[164:165], v[164:165], v[92:93]
	v_pk_mul_f32 v[166:167], v[166:167], v[94:95]
	v_pk_mul_f32 v[168:169], v[168:169], v[88:89]
	v_pk_mul_f32 v[170:171], v[170:171], v[90:91]
	v_pk_mul_f32 v[172:173], v[172:173], v[92:93]
	v_pk_mul_f32 v[174:175], v[174:175], v[94:95]
	v_cvt_pk_bf16_f32 v104, v160, v161
	v_cvt_pk_bf16_f32 v105, v162, v163
	v_cvt_pk_bf16_f32 v106, v164, v165
	v_cvt_pk_bf16_f32 v107, v166, v167
	v_cvt_pk_bf16_f32 v108, v168, v169
	v_cvt_pk_bf16_f32 v109, v170, v171
	v_cvt_pk_bf16_f32 v110, v172, v173
	v_cvt_pk_bf16_f32 v111, v174, v175
	s_nop 1
	v_mfma_f32_32x32x16_bf16 v[16:31], v[60:63], v[104:107], v[16:31]
	v_mfma_f32_32x32x16_bf16 v[0:15], v[60:63], v[108:111], v[0:15]
	s_waitcnt lgkmcnt(0)
	v_lshlrev_b32_e32 v88, 16, v112
	v_lshlrev_b32_e32 v89, 16, v113
	v_lshlrev_b32_e32 v90, 16, v114
	v_lshlrev_b32_e32 v91, 16, v115
	v_lshlrev_b32_e32 v92, 16, v116
	v_lshlrev_b32_e32 v93, 16, v117
	v_lshlrev_b32_e32 v94, 16, v118
	v_lshlrev_b32_e32 v95, 16, v119
	v_pk_mul_f32 v[176:177], v[176:177], v[88:89]
	v_pk_mul_f32 v[178:179], v[178:179], v[90:91]
	v_pk_mul_f32 v[180:181], v[180:181], v[92:93]
	v_pk_mul_f32 v[182:183], v[182:183], v[94:95]
	v_pk_mul_f32 v[184:185], v[184:185], v[88:89]
	v_pk_mul_f32 v[186:187], v[186:187], v[90:91]
	v_pk_mul_f32 v[188:189], v[188:189], v[92:93]
	v_pk_mul_f32 v[190:191], v[190:191], v[94:95]
	v_cvt_pk_bf16_f32 v120, v176, v177
	v_cvt_pk_bf16_f32 v121, v178, v179
	v_cvt_pk_bf16_f32 v122, v180, v181
	v_cvt_pk_bf16_f32 v123, v182, v183
	v_cvt_pk_bf16_f32 v124, v184, v185
	v_cvt_pk_bf16_f32 v125, v186, v187
	v_cvt_pk_bf16_f32 v126, v188, v189
	v_cvt_pk_bf16_f32 v127, v190, v191
	s_nop 1
	v_mfma_f32_32x32x16_bf16 v[16:31], v[56:59], v[120:123], v[16:31]
	v_mfma_f32_32x32x16_bf16 v[0:15], v[56:59], v[124:127], v[0:15]
	s_ashr_i32 s17, s16, 31
	s_lshl_b64 s[38:39], s[16:17], 14
	s_addk_i32 s16, 0x400
	s_ashr_i32 s17, s16, 31
	s_lshl_b64 s[16:17], s[16:17], 14
	v_cvt_pk_bf16_f32 v16, v16, s0
	v_lshl_add_u64 v[56:57], v[72:73], 0, s[38:39]
	s_nop 0
	v_cvt_pk_bf16_f32 v0, v0, s0
	v_lshl_add_u64 v[58:59], v[72:73], 0, s[16:17]
	global_store_short v[56:57], v16, off
	global_store_short v[58:59], v0, off
	v_cvt_pk_bf16_f32 v0, v17, s0
	global_store_short v[56:57], v0, off offset:128
	v_cvt_pk_bf16_f32 v0, v1, s0
	global_store_short v[58:59], v0, off offset:128
	v_cvt_pk_bf16_f32 v0, v18, s0
	global_store_short v[56:57], v0, off offset:256
	v_cvt_pk_bf16_f32 v0, v2, s0
	global_store_short v[58:59], v0, off offset:256
	v_cvt_pk_bf16_f32 v0, v19, s0
	global_store_short v[56:57], v0, off offset:384
	v_cvt_pk_bf16_f32 v0, v3, s0
	global_store_short v[58:59], v0, off offset:384
	v_cvt_pk_bf16_f32 v0, v20, s0
	global_store_short v[56:57], v0, off offset:1024
	v_cvt_pk_bf16_f32 v0, v4, s0
	global_store_short v[58:59], v0, off offset:1024
	v_cvt_pk_bf16_f32 v0, v21, s0
	global_store_short v[56:57], v0, off offset:1152
	v_cvt_pk_bf16_f32 v0, v5, s0
	global_store_short v[58:59], v0, off offset:1152
	v_cvt_pk_bf16_f32 v0, v22, s0
	global_store_short v[56:57], v0, off offset:1280
	v_cvt_pk_bf16_f32 v0, v6, s0
	global_store_short v[58:59], v0, off offset:1280
	v_cvt_pk_bf16_f32 v0, v23, s0
	global_store_short v[56:57], v0, off offset:1408
	v_cvt_pk_bf16_f32 v0, v7, s0
	global_store_short v[58:59], v0, off offset:1408
	v_cvt_pk_bf16_f32 v0, v24, s0
	global_store_short v[56:57], v0, off offset:2048
	v_cvt_pk_bf16_f32 v0, v8, s0
	global_store_short v[58:59], v0, off offset:2048
	v_cvt_pk_bf16_f32 v0, v25, s0
	global_store_short v[56:57], v0, off offset:2176
	v_cvt_pk_bf16_f32 v0, v9, s0
	global_store_short v[58:59], v0, off offset:2176
	v_cvt_pk_bf16_f32 v0, v26, s0
	global_store_short v[56:57], v0, off offset:2304
	v_cvt_pk_bf16_f32 v0, v10, s0
	global_store_short v[58:59], v0, off offset:2304
	v_cvt_pk_bf16_f32 v0, v27, s0
	global_store_short v[56:57], v0, off offset:2432
	v_cvt_pk_bf16_f32 v0, v11, s0
	global_store_short v[58:59], v0, off offset:2432
	v_cvt_pk_bf16_f32 v0, v28, s0
	global_store_short v[56:57], v0, off offset:3072
	v_cvt_pk_bf16_f32 v0, v12, s0
	global_store_short v[58:59], v0, off offset:3072
	v_cvt_pk_bf16_f32 v0, v29, s0
	global_store_short v[56:57], v0, off offset:3200
	v_cvt_pk_bf16_f32 v0, v13, s0
	global_store_short v[58:59], v0, off offset:3200
	v_cvt_pk_bf16_f32 v0, v30, s0
	global_store_short v[56:57], v0, off offset:3328
	v_cvt_pk_bf16_f32 v0, v14, s0
	global_store_short v[58:59], v0, off offset:3328
	v_cvt_pk_bf16_f32 v0, v31, s0
	global_store_short v[56:57], v0, off offset:3456
	v_cvt_pk_bf16_f32 v0, v15, s0
	s_and_b64 vcc, exec, s[18:19]
	s_mov_b32 s16, s22
	global_store_short v[58:59], v0, off offset:3456
	s_barrier
	s_cbranch_vccz .LBB0_748
